# as S12 with the LDS-DMA address arithmetic and issues packed into the first four QK MFMA gaps (earlier prefetch issue), first V-fragment reads in the last four
# speedup vs baseline: 1.0150x; 1.0150x over previous
; #define SBAR() __builtin_amdgcn_sched_barrier(0)
; __device__ __forceinline__ void kload(bf16x8 (&kf)[8], const char* Ks, int r32, int hi, int sb) {
; #pragma unroll
;   for (int d0 = 0; d0 < 4; ++d0) { const int cb = sb + (d0 * 16 + hi * 8) * 2;
;     kf[2 * d0] = *reinterpret_cast<const bf16x8*>(Ks + KSWZ(r32, cb)); kf[2 * d0 + 1] = *reinterpret_cast<const bf16x8*>(Ks + KSWZ(32 + r32, cb)); }
; }
; __device__ __forceinline__ void kmma(f32x16& p0, f32x16& p1, const bf16x8 (&kf)[8], const bf16x8* qr) {
;   asm volatile("s_waitcnt lgkmcnt(0)" ::: "memory"); SBAR();
;   p0 = f32x16{}; p1 = f32x16{};
; #pragma unroll
;   for (int d0 = 0; d0 < 4; ++d0) { p0 = __builtin_amdgcn_mfma_f32_32x32x16_bf16(kf[2 * d0], qr[d0], p0, 0, 0, 0); p1 = __builtin_amdgcn_mfma_f32_32x32x16_bf16(kf[2 * d0 + 1], qr[d0], p1, 0, 0, 0); }
; }
; __device__ __forceinline__ void qkt(f32x16& p0, f32x16& p1, const char* Ks, const bf16x8* qr, int r32, int hi, int sb) {
;   bf16x8 kf[8]; kload(kf, Ks, r32, hi, sb); SBAR(); kmma(p0, p1, kf, qr);
; }
.LBB0_770:
	ds_read_b128 v[82:85], v245
	ds_read_b128 v[86:89], v245 offset:8192
	ds_read_b128 v[130:133], v246
	ds_read_b128 v[134:137], v246 offset:8192
	ds_read_b128 v[206:209], v247
	ds_read_b128 v[210:213], v247 offset:8192
	ds_read_b128 v[214:217], v255
	ds_read_b128 v[218:221], v255 offset:8192
	v_exp_f32_e32 v148, v66
	v_add_f32_e32 v66, 0, v175
	v_add_f32_e32 v66, v177, v66
	v_add_f32_e32 v66, v192, v66
	v_add_f32_e32 v66, v195, v66
	v_add_f32_e32 v66, v196, v66
	v_add_f32_e32 v66, v199, v66
	v_add_f32_e32 v66, v200, v66
	v_add_f32_e32 v66, v203, v66
	v_add_f32_e32 v66, v176, v66
	v_add_f32_e32 v66, v193, v66
	v_add_f32_e32 v66, v194, v66
	v_add_f32_e32 v66, v197, v66
	v_add_f32_e32 v66, v198, v66
	v_exp_f32_e32 v149, v67
	v_add_f32_e32 v66, v201, v66
	s_waitcnt lgkmcnt(7)
	v_mfma_f32_32x32x16_bf16 v[98:113], v[82:85], v[126:129], 0
	s_add_i32 s37, s12, 2
	v_exp_f32_e32 v150, v68
	s_cmpk_lt_u32 s12, 0x7e
	v_add_f32_e32 v66, v202, v66
	s_cselect_b64 s[0:1], -1, 0
	v_exp_f32_e32 v151, v69
	s_and_b64 s[10:11], s[0:1], exec
	v_add_f32_e32 v66, v204, v66
	s_cselect_b32 s10, 0, 0xffffff80
	s_add_i32 s58, s37, s10
	s_and_b64 s[0:1], s[0:1], exec
	s_cselect_b32 s1, s9, s30
	s_cselect_b32 s0, s8, s26
	s_lshl_b64 s[10:11], s[58:59], 17
	s_waitcnt lgkmcnt(6)
	v_mfma_f32_32x32x16_bf16 v[82:97], v[86:89], v[126:129], 0
	s_lshl_b64 s[0:1], s[0:1], 11
	v_exp_f32_e32 v186, v70
	s_add_u32 s10, s10, s0
	v_add_f32_e32 v66, v148, v66
	s_addc_u32 s11, s11, s1
	v_exp_f32_e32 v187, v71
	s_add_u32 s0, s20, s10
	v_add_f32_e32 v66, v149, v66
	s_addc_u32 s1, s21, s11
	v_exp_f32_e32 v188, v72
	s_add_u32 s10, s22, s10
	s_addc_u32 s11, s23, s11
	s_and_b32 s13, s37, 0xff
	s_mulk_i32 s13, 0xab
	s_lshr_b32 s13, s13, 9
	s_waitcnt lgkmcnt(5)
	v_mfma_f32_32x32x16_bf16 v[98:113], v[130:133], v[122:125], v[98:113]
	s_mul_i32 s13, s13, 3
	v_add_f32_e32 v66, v150, v66
	s_sub_i32 s13, s37, s13
	v_exp_f32_e32 v189, v73
	s_and_b32 s13, s13, 0xff
	v_add_f32_e32 v66, v151, v66
	s_lshl_b32 s13, s13, 14
	s_mov_b32 s100, s13
	v_exp_f32_e32 v205, v74
	s_add_i32 s42, s36, 0xffffc000
	s_and_b32 s42, s42, 0xc000
	s_add_i32 s13, s13, s27
	s_add_i32 s42, s42, s31
	v_lshl_add_u64 v[246:247], s[0:1], 0, v[146:147]
	s_mov_b32 m0, s13
	s_waitcnt lgkmcnt(4)
	v_mfma_f32_32x32x16_bf16 v[82:97], v[134:137], v[122:125], v[82:97]
	global_load_lds_dwordx4 v[246:247], off
	v_add_f32_e32 v66, v186, v66
	v_lshl_add_u64 v[246:247], s[10:11], 0, v[142:143]
	v_exp_f32_e32 v222, v75
	s_mov_b32 m0, s42
	v_add_f32_e32 v66, v187, v66
	global_load_lds_dwordx4 v[246:247], off
	v_exp_f32_e32 v223, v76
	v_lshl_add_u64 v[246:247], s[0:1], 0, v[144:145]
	v_add_f32_e32 v66, v188, v66
	s_add_i32 m0, s13, 0x2000
	s_nop 0
	global_load_lds_dwordx4 v[246:247], off
	v_lshl_add_u64 v[246:247], s[10:11], 0, v[154:155]
	s_add_i32 m0, s42, 0x2000
	s_nop 0
	global_load_lds_dwordx4 v[246:247], off
	s_waitcnt lgkmcnt(3)
	v_mfma_f32_32x32x16_bf16 v[98:113], v[206:209], v[118:121], v[98:113]
	s_and_b32 s13, s36, 0xc000
	v_exp_f32_e32 v224, v77
	v_add_u32_e32 v244, s13, v164
	v_add_f32_e32 v66, v189, v66
	v_exp_f32_e32 v225, v78
	v_add_f32_e32 v66, v205, v66
	s_waitcnt lgkmcnt(2)
	v_mfma_f32_32x32x16_bf16 v[82:97], v[210:213], v[118:121], v[82:97]
	ds_read_b64_tr_b16 v[228:229], v244 offset:0
	v_exp_f32_e32 v226, v79
	ds_read_b64_tr_b16 v[230:231], v244 offset:0x800
	v_add_f32_e32 v66, v222, v66
	ds_read_b64_tr_b16 v[232:233], v244 offset:0x1000
	v_exp_f32_e32 v227, v80
	v_add_f32_e32 v66, v223, v66
	v_exp_f32_e32 v81, v81
	s_waitcnt lgkmcnt(4)
	v_mfma_f32_32x32x16_bf16 v[98:113], v[214:217], v[114:117], v[98:113]
	ds_read_b64_tr_b16 v[234:235], v244 offset:0x1800
	v_add_f32_e32 v66, v224, v66
	ds_read_b64_tr_b16 v[236:237], v244 offset:0x2000
	v_add_f32_e32 v66, v225, v66
	v_add_f32_e32 v66, v226, v66
	v_add_f32_e32 v66, v227, v66
	s_waitcnt lgkmcnt(5)
	v_mfma_f32_32x32x16_bf16 v[82:97], v[218:221], v[114:117], v[82:97]
	ds_read_b64_tr_b16 v[238:239], v244 offset:0x2800
	v_add_f32_e32 v130, v81, v66
	ds_read_b64_tr_b16 v[240:241], v244 offset:0x3000
	v_mov_b32_e32 v131, v130
	ds_read_b64_tr_b16 v[242:243], v244 offset:0x3800
	v_cvt_pk_bf16_f32 v66, v175, v177
	v_cvt_pk_bf16_f32 v67, v192, v195
	v_cvt_pk_bf16_f32 v68, v196, v199
	v_permlane32_swap_b32_e32 v130, v131
	v_cvt_pk_bf16_f32 v69, v200, v203
	v_permlane32_swap_b32_e32 v66, v68
	v_cvt_pk_bf16_f32 v70, v176, v193
	v_cvt_pk_bf16_f32 v71, v194, v197
	v_cvt_pk_bf16_f32 v72, v198, v201
	v_cvt_pk_bf16_f32 v73, v202, v204
	v_cvt_pk_bf16_f32 v74, v148, v149
	v_cvt_pk_bf16_f32 v75, v150, v151
	v_cvt_pk_bf16_f32 v76, v186, v187
	v_cvt_pk_bf16_f32 v77, v188, v189
	v_cvt_pk_bf16_f32 v78, v205, v222
	v_cvt_pk_bf16_f32 v79, v223, v224
	v_cvt_pk_bf16_f32 v80, v225, v226
	v_cvt_pk_bf16_f32 v81, v227, v81
	v_permlane32_swap_b32_e32 v67, v69
	v_permlane32_swap_b32_e32 v70, v72
	v_permlane32_swap_b32_e32 v71, v73
	v_permlane32_swap_b32_e32 v74, v76
	v_permlane32_swap_b32_e32 v75, v77
	v_permlane32_swap_b32_e32 v78, v80
	v_permlane32_swap_b32_e32 v79, v81
	ds_read_b64_tr_b16 v[204:205], v244 offset:0x200
	ds_read_b64_tr_b16 v[206:207], v244 offset:0xa00
	ds_read_b64_tr_b16 v[208:209], v244 offset:0x1200
	ds_read_b64_tr_b16 v[210:211], v244 offset:0x1a00
	ds_read_b64_tr_b16 v[212:213], v244 offset:0x2200
	ds_read_b64_tr_b16 v[214:215], v244 offset:0x2a00
	ds_read_b64_tr_b16 v[216:217], v244 offset:0x3200
	ds_read_b64_tr_b16 v[218:219], v244 offset:0x3a00
	s_waitcnt lgkmcnt(14)
	v_mfma_f32_32x32x16_bf16 v[18:33], v[66:69], v[228:231], v[18:33]
	v_max_f32_e32 v245, v99, v99
	v_max_f32_e32 v246, v98, v98
	v_max_f32_e32 v245, v246, v245
	v_max3_f32 v245, v245, v100, v101
	v_max3_f32 v245, v245, v102, v103
	v_max3_f32 v245, v245, v104, v105
	v_max3_f32 v245, v245, v106, v107
	v_max3_f32 v245, v245, v108, v109
	s_waitcnt lgkmcnt(12)
; #define SBAR() __builtin_amdgcn_sched_barrier(0)
; __device__ __forceinline__ void partialSM(f32x16& p0, f32x16& p1, float& m_reg, float& mn, float& alpha) {
;   constexpr float C = SCALE * 1.4426950408889634f;
;   float pmax = p0[0]; for (int r = 1; r < 16; ++r) pmax = fmaxf(pmax, p0[r]); for (int r = 0; r < 16; ++r) pmax = fmaxf(pmax, p1[r]);
;   { auto rr = __builtin_amdgcn_permlane32_swap(__float_as_uint(pmax), __float_as_uint(pmax), false, false);
;     pmax = fmaxf(__uint_as_float(rr[0]), __uint_as_float(rr[1])); }
;   if (__builtin_expect(__all(pmax - m_reg <= THR / SCALE), 1)) { mn = m_reg; alpha = 1.f; }
;   else { mn = fmaxf(m_reg, pmax); alpha = __builtin_amdgcn_exp2f((m_reg - mn) * C); m_reg = mn; }
;   float mnC = -mn * C;
;   for (int r = 0; r < 16; ++r) p0[r] = fmaf(p0[r], C, mnC); for (int r = 0; r < 16; ++r) p1[r] = fmaf(p1[r], C, mnC);
;   for (int r = 0; r < 16; ++r) p0[r] = __builtin_amdgcn_exp2f(p0[r]);
; }
; __device__ __forceinline__ void pv_d0(f32x16* o, int vb, bf16x8 pa0, bf16x8 pa1, bf16x8 pa2, bf16x8 pa3) {
;   VFrag fa, fb;
;   v_frag_read<0>(fa, vb);
;   asm volatile("s_waitcnt lgkmcnt(0)" ::: "memory"); SBAR();
;   v_frag_read<1>(fb, vb); SBAR();
;   pv_mma(o[0], fa, pa0, pa1, pa2, pa3); SBAR();
;   asm volatile("s_waitcnt lgkmcnt(0)" ::: "memory"); SBAR();
;   v_frag_read<2>(fa, vb); SBAR();
;   pv_mma(o[1], fb, pa0, pa1, pa2, pa3); SBAR();
;   asm volatile("s_waitcnt lgkmcnt(0)" ::: "memory"); SBAR();
;   v_frag_read<3>(fb, vb); SBAR();
;   pv_mma(o[2], fa, pa0, pa1, pa2, pa3); SBAR();
;   asm volatile("s_waitcnt lgkmcnt(0)" ::: "memory"); SBAR();
;   pv_mma(o[3], fb, pa0, pa1, pa2, pa3);
; }
	v_mfma_f32_32x32x16_bf16 v[18:33], v[70:73], v[232:235], v[18:33]
	v_max3_f32 v245, v245, v110, v111
	v_max3_f32 v245, v245, v112, v113
	v_max3_f32 v245, v245, v82, v83
	v_max3_f32 v245, v245, v84, v85
	v_max3_f32 v245, v245, v86, v87
	v_max3_f32 v245, v245, v88, v89
	v_max3_f32 v245, v245, v90, v91
	v_max3_f32 v245, v245, v92, v93
	s_waitcnt lgkmcnt(10)
	v_mfma_f32_32x32x16_bf16 v[18:33], v[74:77], v[236:239], v[18:33]
	v_max3_f32 v245, v245, v94, v95
	v_max3_f32 v245, v245, v96, v97
	v_mov_b32_e32 v246, v245
	s_nop 1
	v_permlane32_swap_b32_e32 v245, v246
	v_max_f32_e32 v246, v246, v246
	v_max_f32_e32 v245, v245, v245
	v_max_f32_e32 v245, v245, v246
	v_sub_f32_e32 v246, v245, v174
	s_waitcnt lgkmcnt(8)
	v_mfma_f32_32x32x16_bf16 v[18:33], v[78:81], v[240:243], v[18:33]
	v_cmp_ge_f32_e32 vcc, s63, v246
	v_max_f32_e32 v246, v174, v174
	v_max_f32_e32 v245, v246, v245
	v_sub_f32_e32 v246, v174, v245
	v_mul_f32_e32 v246, 0x3e38aa3b, v246
	v_exp_f32_e32 v246, v246
	s_cmp_eq_u64 vcc, exec
	s_cselect_b64 s[0:1], -1, 0
	v_cndmask_b32_e64 v132, v246, 1.0, s[0:1]
	ds_read_b64_tr_b16 v[228:229], v244 offset:0x400
	ds_read_b64_tr_b16 v[230:231], v244 offset:0xc00
	ds_read_b64_tr_b16 v[232:233], v244 offset:0x1400
	ds_read_b64_tr_b16 v[234:235], v244 offset:0x1c00
	ds_read_b64_tr_b16 v[236:237], v244 offset:0x2400
	ds_read_b64_tr_b16 v[238:239], v244 offset:0x2c00
	ds_read_b64_tr_b16 v[240:241], v244 offset:0x3400
	ds_read_b64_tr_b16 v[242:243], v244 offset:0x3c00
	v_cndmask_b32_e64 v133, v245, v174, s[0:1]
	v_mul_f32_e32 v148, 0xbe38aa3b, v133
	s_waitcnt lgkmcnt(14)
	v_mfma_f32_32x32x16_bf16 v[50:65], v[66:69], v[204:207], v[50:65]
	v_fmamk_f32 v98, v98, 0x3e38aa3b, v148
	v_fmamk_f32 v99, v99, 0x3e38aa3b, v148
	v_fmamk_f32 v100, v100, 0x3e38aa3b, v148
	v_fmamk_f32 v101, v101, 0x3e38aa3b, v148
	s_waitcnt lgkmcnt(12)
	v_mfma_f32_32x32x16_bf16 v[50:65], v[70:73], v[208:211], v[50:65]
	v_fmamk_f32 v102, v102, 0x3e38aa3b, v148
	v_fmamk_f32 v103, v103, 0x3e38aa3b, v148
	v_fmamk_f32 v104, v104, 0x3e38aa3b, v148
	v_fmamk_f32 v105, v105, 0x3e38aa3b, v148
	s_waitcnt lgkmcnt(10)
	v_mfma_f32_32x32x16_bf16 v[50:65], v[74:77], v[212:215], v[50:65]
	v_fmamk_f32 v106, v106, 0x3e38aa3b, v148
	v_fmamk_f32 v107, v107, 0x3e38aa3b, v148
	v_fmamk_f32 v108, v108, 0x3e38aa3b, v148
	v_fmamk_f32 v109, v109, 0x3e38aa3b, v148
	s_waitcnt lgkmcnt(8)
	v_mfma_f32_32x32x16_bf16 v[50:65], v[78:81], v[216:219], v[50:65]
	v_fmamk_f32 v110, v110, 0x3e38aa3b, v148
	v_fmamk_f32 v111, v111, 0x3e38aa3b, v148
	v_fmamk_f32 v112, v112, 0x3e38aa3b, v148
	v_fmamk_f32 v113, v113, 0x3e38aa3b, v148
	ds_read_b64_tr_b16 v[204:205], v244 offset:0x600
	ds_read_b64_tr_b16 v[206:207], v244 offset:0xe00
	ds_read_b64_tr_b16 v[208:209], v244 offset:0x1600
	ds_read_b64_tr_b16 v[210:211], v244 offset:0x1e00
	ds_read_b64_tr_b16 v[212:213], v244 offset:0x2600
	ds_read_b64_tr_b16 v[214:215], v244 offset:0x2e00
	ds_read_b64_tr_b16 v[216:217], v244 offset:0x3600
	ds_read_b64_tr_b16 v[218:219], v244 offset:0x3e00
	s_waitcnt lgkmcnt(14)
	v_mfma_f32_32x32x16_bf16 v[34:49], v[66:69], v[228:231], v[34:49]
	v_fmamk_f32 v82, v82, 0x3e38aa3b, v148
	v_fmamk_f32 v83, v83, 0x3e38aa3b, v148
	v_fmamk_f32 v84, v84, 0x3e38aa3b, v148
	v_fmamk_f32 v85, v85, 0x3e38aa3b, v148
	s_waitcnt lgkmcnt(12)
	v_mfma_f32_32x32x16_bf16 v[34:49], v[70:73], v[232:235], v[34:49]
	v_fmamk_f32 v86, v86, 0x3e38aa3b, v148
	v_fmamk_f32 v87, v87, 0x3e38aa3b, v148
	s_add_i32 s13, s36, 0xffff4000
	v_fmamk_f32 v149, v88, 0x3e38aa3b, v148
	s_waitcnt lgkmcnt(10)
	v_mfma_f32_32x32x16_bf16 v[34:49], v[74:77], v[236:239], v[34:49]
	v_fmamk_f32 v150, v89, 0x3e38aa3b, v148
	v_fmamk_f32 v151, v90, 0x3e38aa3b, v148
	v_fmamk_f32 v186, v91, 0x3e38aa3b, v148
	v_fmamk_f32 v187, v92, 0x3e38aa3b, v148
	s_waitcnt lgkmcnt(8)
	v_mfma_f32_32x32x16_bf16 v[34:49], v[78:81], v[240:243], v[34:49]
	v_fmamk_f32 v188, v93, 0x3e38aa3b, v148
	v_fmamk_f32 v189, v94, 0x3e38aa3b, v148
	v_exp_f32_e32 v192, v98
	v_exp_f32_e32 v193, v99
	v_exp_f32_e32 v194, v100
	v_exp_f32_e32 v195, v101
	s_waitcnt lgkmcnt(6)
	v_mfma_f32_32x32x16_bf16 v[2:17], v[66:69], v[204:207], v[2:17]
	v_exp_f32_e32 v196, v102
	v_exp_f32_e32 v197, v103
	v_exp_f32_e32 v198, v104
	v_exp_f32_e32 v199, v105
	s_waitcnt lgkmcnt(4)
	v_mfma_f32_32x32x16_bf16 v[2:17], v[70:73], v[208:211], v[2:17]
	v_exp_f32_e32 v200, v106
	v_exp_f32_e32 v201, v107
	v_exp_f32_e32 v202, v108
	v_exp_f32_e32 v203, v109
	v_exp_f32_e32 v204, v110
	v_exp_f32_e32 v205, v111
	s_waitcnt lgkmcnt(2)
	v_mfma_f32_32x32x16_bf16 v[2:17], v[74:77], v[212:215], v[2:17]
	v_exp_f32_e32 v206, v112
	v_exp_f32_e32 v207, v113
	v_fmamk_f32 v208, v95, 0x3e38aa3b, v148
	v_fmamk_f32 v209, v96, 0x3e38aa3b, v148
	v_fmac_f32_e32 v148, 0x3e38aa3b, v97
	s_waitcnt lgkmcnt(0)
	v_mfma_f32_32x32x16_bf16 v[2:17], v[78:81], v[216:219], v[2:17]
	v_add_u32_e32 v245, s101, v169
	v_add_u32_e32 v246, s101, v170
	v_add_u32_e32 v247, s101, v171
	v_add_u32_e32 v244, s101, v172
	v_cmp_gt_f32_e32 vcc, 1.0, v132
	s_cbranch_vccz .LBB0_774
	s_and_saveexec_b64 s[10:11], s[40:41]
	ds_write_b32 v162, v132 offset:128
	s_or_b64 exec, exec, s[10:11]
	s_waitcnt lgkmcnt(0)
	v_add_u32_e32 v67, s18, v140
	ds_read_b128 v[68:71], v67 offset:224
	ds_read_b128 v[72:75], v67 offset:192
	ds_read_b128 v[76:79], v67 offset:160
	ds_read_b128 v[134:137], v67 offset:128
	s_waitcnt lgkmcnt(0)
	v_pk_mul_f32 v[30:31], v[30:31], v[68:69]
	v_pk_mul_f32 v[26:27], v[26:27], v[72:73]
	v_pk_mul_f32 v[22:23], v[22:23], v[76:77]
	v_pk_mul_f32 v[32:33], v[32:33], v[70:71]
	v_pk_mul_f32 v[28:29], v[28:29], v[74:75]
	v_pk_mul_f32 v[24:25], v[24:25], v[78:79]
	v_pk_mul_f32 v[20:21], v[20:21], v[136:137]
	v_pk_mul_f32 v[18:19], v[18:19], v[134:135]
	v_pk_mul_f32 v[62:63], v[62:63], v[68:69]
	v_pk_mul_f32 v[58:59], v[58:59], v[72:73]
	v_pk_mul_f32 v[54:55], v[54:55], v[76:77]
	v_pk_mul_f32 v[64:65], v[64:65], v[70:71]
	v_pk_mul_f32 v[60:61], v[60:61], v[74:75]
	v_pk_mul_f32 v[56:57], v[56:57], v[78:79]
	v_pk_mul_f32 v[52:53], v[52:53], v[136:137]
	v_pk_mul_f32 v[50:51], v[50:51], v[134:135]
	v_pk_mul_f32 v[46:47], v[46:47], v[68:69]
	v_pk_mul_f32 v[42:43], v[42:43], v[72:73]
	v_pk_mul_f32 v[38:39], v[38:39], v[76:77]
	v_pk_mul_f32 v[48:49], v[48:49], v[70:71]
	v_pk_mul_f32 v[44:45], v[44:45], v[74:75]
	v_pk_mul_f32 v[40:41], v[40:41], v[78:79]
	v_pk_mul_f32 v[36:37], v[36:37], v[136:137]
	v_pk_mul_f32 v[34:35], v[34:35], v[134:135]
	v_pk_mul_f32 v[14:15], v[14:15], v[68:69]
	v_pk_mul_f32 v[10:11], v[10:11], v[72:73]
	v_pk_mul_f32 v[6:7], v[6:7], v[76:77]
	v_pk_mul_f32 v[16:17], v[16:17], v[70:71]
	v_pk_mul_f32 v[12:13], v[12:13], v[74:75]
	v_pk_mul_f32 v[8:9], v[8:9], v[78:79]
	v_pk_mul_f32 v[4:5], v[4:5], v[136:137]
	v_pk_mul_f32 v[2:3], v[2:3], v[134:135]
; #define SBAR() __builtin_amdgcn_sched_barrier(0)
; __device__ __forceinline__ void kload(bf16x8 (&kf)[8], const char* Ks, int r32, int hi, int sb) {
; #pragma unroll
;   for (int d0 = 0; d0 < 4; ++d0) { const int cb = sb + (d0 * 16 + hi * 8) * 2;
;     kf[2 * d0] = *reinterpret_cast<const bf16x8*>(Ks + KSWZ(r32, cb)); kf[2 * d0 + 1] = *reinterpret_cast<const bf16x8*>(Ks + KSWZ(32 + r32, cb)); }
; }
; __device__ __forceinline__ void kmma(f32x16& p0, f32x16& p1, const bf16x8 (&kf)[8], const bf16x8* qr) {
;   asm volatile("s_waitcnt lgkmcnt(0)" ::: "memory"); SBAR();
;   p0 = f32x16{}; p1 = f32x16{};
; #pragma unroll
;   for (int d0 = 0; d0 < 4; ++d0) { p0 = __builtin_amdgcn_mfma_f32_32x32x16_bf16(kf[2 * d0], qr[d0], p0, 0, 0, 0); p1 = __builtin_amdgcn_mfma_f32_32x32x16_bf16(kf[2 * d0 + 1], qr[d0], p1, 0, 0, 0); }
; }
; __device__ __forceinline__ void qkt(f32x16& p0, f32x16& p1, const char* Ks, const bf16x8* qr, int r32, int hi, int sb) {
;   bf16x8 kf[8]; kload(kf, Ks, r32, hi, sb); SBAR(); kmma(p0, p1, kf, qr);
; }
.LBB0_774:
	s_waitcnt vmcnt(4)
	s_barrier
	ds_read_b128 v[66:69], v245
	ds_read_b128 v[70:73], v245 offset:8192
	ds_read_b128 v[98:101], v246
	ds_read_b128 v[102:105], v246 offset:8192
	ds_read_b128 v[106:109], v247
	ds_read_b128 v[110:113], v247 offset:8192
	ds_read_b128 v[134:137], v244
	ds_read_b128 v[174:177], v244 offset:8192
	v_exp_f32_e32 v210, v82
	v_exp_f32_e32 v211, v83
	v_exp_f32_e32 v212, v84
	v_exp_f32_e32 v213, v85
	v_exp_f32_e32 v214, v86
	v_exp_f32_e32 v215, v87
	v_add_f32_e32 v216, 0, v192
	v_add_f32_e32 v216, v193, v216
	v_add_f32_e32 v216, v194, v216
	v_add_f32_e32 v216, v195, v216
	v_exp_f32_e32 v149, v149
	v_exp_f32_e32 v150, v150
	v_exp_f32_e32 v151, v151
	v_exp_f32_e32 v186, v186
	v_exp_f32_e32 v187, v187
	v_exp_f32_e32 v188, v188
	s_waitcnt lgkmcnt(7)
	v_mfma_f32_32x32x16_bf16 v[82:97], v[66:69], v[126:129], 0
	s_add_i32 s46, s12, 3
	v_exp_f32_e32 v189, v189
	s_cmpk_lt_u32 s12, 0x7d
	v_exp_f32_e32 v208, v208
	s_cselect_b64 s[42:43], -1, 0
	v_exp_f32_e32 v209, v209
	s_and_b64 s[44:45], s[42:43], exec
	v_exp_f32_e32 v148, v148
	s_cselect_b32 s44, 0, 0xffffff80
	s_add_i32 s58, s46, s44
	s_and_b64 s[42:43], s[42:43], exec
	s_cselect_b32 s43, s9, s30
	s_waitcnt lgkmcnt(6)
	v_mfma_f32_32x32x16_bf16 v[66:81], v[70:73], v[126:129], 0
	s_cselect_b32 s42, s8, s26
	v_add_f32_e32 v255, v196, v216
	s_lshl_b64 s[44:45], s[58:59], 17
	v_add_f32_e32 v255, v197, v255
	s_lshl_b64 s[42:43], s[42:43], 11
	v_add_f32_e32 v255, v198, v255
	s_add_u32 s44, s44, s42
	v_add_f32_e32 v255, v199, v255
	s_addc_u32 s45, s45, s43
	v_add_f32_e32 v255, v200, v255
	s_add_u32 s42, s20, s44
	s_addc_u32 s43, s21, s45
	s_add_u32 s44, s22, s44
	s_mul_i32 s47, s46, 0xab
	s_waitcnt lgkmcnt(5)
	v_mfma_f32_32x32x16_bf16 v[82:97], v[98:101], v[122:125], v[82:97]
	s_addc_u32 s45, s23, s45
	v_add_f32_e32 v255, v201, v255
	s_bfe_u32 s47, s47, 0x70009
	v_add_f32_e32 v255, v202, v255
	s_mul_i32 s47, s47, 3
	v_add_f32_e32 v255, v203, v255
	s_sub_i32 s46, s46, s47
	v_add_f32_e32 v255, v204, v255
	s_and_b32 s46, s46, 0xff
	s_lshl_b32 s46, s46, 14
	s_mov_b32 s101, s46
	s_add_i32 s46, s46, s27
	s_and_b32 s47, s36, 0xc000
	s_add_i32 s47, s47, s31
	s_waitcnt lgkmcnt(4)
	v_mfma_f32_32x32x16_bf16 v[66:81], v[102:105], v[122:125], v[66:81]
	s_and_b32 s0, s13, 0xc000
	v_add_f32_e32 v255, v205, v255
	v_add_u32_e32 v244, s0, v164
	v_add_f32_e32 v255, v206, v255
	v_add_f32_e32 v255, v207, v255
	v_add_f32_e32 v255, v210, v255
	v_add_f32_e32 v255, v211, v255
	s_waitcnt lgkmcnt(3)
	v_mfma_f32_32x32x16_bf16 v[82:97], v[106:109], v[118:121], v[82:97]
	ds_read_b64_tr_b16 v[228:229], v244 offset:0
	v_add_f32_e32 v255, v212, v255
	ds_read_b64_tr_b16 v[230:231], v244 offset:0x800
	v_add_f32_e32 v255, v213, v255
	ds_read_b64_tr_b16 v[232:233], v244 offset:0x1000
	v_add_f32_e32 v255, v214, v255
	v_add_f32_e32 v255, v215, v255
	s_waitcnt lgkmcnt(5)
	v_mfma_f32_32x32x16_bf16 v[66:81], v[110:113], v[118:121], v[66:81]
	ds_read_b64_tr_b16 v[234:235], v244 offset:0x1800
	v_add_f32_e32 v255, v149, v255
	ds_read_b64_tr_b16 v[236:237], v244 offset:0x2000
	v_add_f32_e32 v255, v150, v255
	v_add_f32_e32 v255, v151, v255
	v_add_f32_e32 v255, v186, v255
	v_add_f32_e32 v255, v187, v255
	s_waitcnt lgkmcnt(6)
	v_mfma_f32_32x32x16_bf16 v[82:97], v[134:137], v[114:117], v[82:97]
	ds_read_b64_tr_b16 v[238:239], v244 offset:0x2800
	v_add_f32_e32 v255, v188, v255
	ds_read_b64_tr_b16 v[240:241], v244 offset:0x3000
	v_add_f32_e32 v255, v189, v255
	ds_read_b64_tr_b16 v[242:243], v244 offset:0x3800
	v_add_f32_e32 v255, v208, v255
	v_add_f32_e32 v255, v209, v255
	v_add_f32_e32 v99, v148, v255
	s_cmpk_gt_u32 s12, 0x80
	s_cselect_b64 s[10:11], -1, 0
	s_and_b64 vcc, exec, s[10:11]
	s_cbranch_vccnz .LBB0_776
	v_lshl_add_u64 v[246:247], s[42:43], 0, v[146:147]
	s_mov_b32 m0, s46
	s_nop 0
	global_load_lds_dwordx4 v[246:247], off
	v_lshl_add_u64 v[246:247], s[44:45], 0, v[142:143]
	s_mov_b32 m0, s47
	s_nop 0
	global_load_lds_dwordx4 v[246:247], off
	v_lshl_add_u64 v[246:247], s[42:43], 0, v[144:145]
	s_add_i32 m0, s46, 0x2000
	s_nop 0
	global_load_lds_dwordx4 v[246:247], off
	v_lshl_add_u64 v[246:247], s[44:45], 0, v[154:155]
	s_add_i32 m0, s47, 0x2000
	s_nop 0
	global_load_lds_dwordx4 v[246:247], off
